# phase-0 pinned K-loop MFMA blocks + P1/P9 per-round tile rotation (balanced heavy/light epilogues per WG)
# baseline (speedup 1.0000x reference)
.LBB0_217:
	s_add_u32 s36, s34, 0xfffc0080
	s_addc_u32 s37, s35, -1
	s_cmp_eq_u32 s71, 12
	s_cselect_b32 s39, s7, s37
	s_cselect_b32 s38, s25, s36
	s_cselect_b32 s37, s23, s70
	s_cselect_b32 s36, s68, s69
	v_lshl_add_u64 v[150:151], s[34:35], 0, v[138:139]
	s_add_i32 m0, s31, 0xc000
	s_nop 0
	global_load_lds_dwordx4 v[150:151], off
	v_lshl_add_u64 v[150:151], s[34:35], 0, v[140:141]
	s_add_i32 m0, s31, 0xe000
	s_nop 0
	global_load_lds_dwordx4 v[150:151], off
	ds_read_b128 v[146:149], v155
	ds_read_b128 v[158:161], v155 offset:1024
	ds_read_b128 v[162:165], v155 offset:2048
	ds_read_b128 v[166:169], v155 offset:3072
	ds_read_b128 v[170:173], v156
	ds_read_b128 v[174:177], v156 offset:1024
	ds_read_b128 v[178:181], v156 offset:2048
	ds_read_b128 v[182:185], v156 offset:3072
	ds_read_b128 v[186:189], v157
	ds_read_b128 v[190:193], v157 offset:1024
	ds_read_b128 v[194:197], v157 offset:2048
	ds_read_b128 v[198:201], v157 offset:3072
	ds_read_b128 v[202:205], v157 offset:4096
	ds_read_b128 v[206:209], v157 offset:5120
	ds_read_b128 v[210:213], v157 offset:6144
	ds_read_b128 v[214:217], v157 offset:7168
	s_nop 0
	s_waitcnt vmcnt(8)
	s_waitcnt lgkmcnt(0)
	s_setprio 1
	s_barrier
	v_mfma_f32_16x16x32_bf16 v[124:127], v[146:149], v[186:189], v[124:127]
	v_mfma_f32_16x16x32_bf16 v[120:123], v[162:165], v[186:189], v[120:123]
	v_mfma_f32_16x16x32_bf16 v[108:111], v[146:149], v[194:197], v[108:111]
	v_mfma_f32_16x16x32_bf16 v[104:107], v[162:165], v[194:197], v[104:107]
	v_mfma_f32_16x16x32_bf16 v[92:95], v[146:149], v[202:205], v[92:95]
	v_mfma_f32_16x16x32_bf16 v[88:91], v[162:165], v[202:205], v[88:91]
	v_mfma_f32_16x16x32_bf16 v[76:79], v[146:149], v[210:213], v[76:79]
	v_mfma_f32_16x16x32_bf16 v[72:75], v[162:165], v[210:213], v[72:75]
	v_mfma_f32_16x16x32_bf16 v[124:127], v[158:161], v[190:193], v[124:127]
	v_mfma_f32_16x16x32_bf16 v[120:123], v[166:169], v[190:193], v[120:123]
	v_mfma_f32_16x16x32_bf16 v[108:111], v[158:161], v[198:201], v[108:111]
	v_mfma_f32_16x16x32_bf16 v[104:107], v[166:169], v[198:201], v[104:107]
	v_mfma_f32_16x16x32_bf16 v[92:95], v[158:161], v[206:209], v[92:95]
	v_mfma_f32_16x16x32_bf16 v[88:91], v[166:169], v[206:209], v[88:91]
	v_mfma_f32_16x16x32_bf16 v[76:79], v[158:161], v[214:217], v[76:79]
	v_mfma_f32_16x16x32_bf16 v[72:75], v[166:169], v[214:217], v[72:75]
	s_setprio 0
	s_setprio 1
	v_mfma_f32_16x16x32_bf16 v[116:119], v[170:173], v[186:189], v[116:119]
	v_mfma_f32_16x16x32_bf16 v[112:115], v[178:181], v[186:189], v[112:115]
	v_mfma_f32_16x16x32_bf16 v[100:103], v[170:173], v[194:197], v[100:103]
	v_mfma_f32_16x16x32_bf16 v[96:99], v[178:181], v[194:197], v[96:99]
	v_mfma_f32_16x16x32_bf16 v[84:87], v[170:173], v[202:205], v[84:87]
	v_mfma_f32_16x16x32_bf16 v[80:83], v[178:181], v[202:205], v[80:83]
	v_mfma_f32_16x16x32_bf16 v[68:71], v[170:173], v[210:213], v[68:71]
	v_mfma_f32_16x16x32_bf16 v[64:67], v[178:181], v[210:213], v[64:67]
	v_mfma_f32_16x16x32_bf16 v[116:119], v[174:177], v[190:193], v[116:119]
	v_mfma_f32_16x16x32_bf16 v[112:115], v[182:185], v[190:193], v[112:115]
	v_mfma_f32_16x16x32_bf16 v[100:103], v[174:177], v[198:201], v[100:103]
	v_mfma_f32_16x16x32_bf16 v[96:99], v[182:185], v[198:201], v[96:99]
	v_mfma_f32_16x16x32_bf16 v[84:87], v[174:177], v[206:209], v[84:87]
	v_mfma_f32_16x16x32_bf16 v[80:83], v[182:185], v[206:209], v[80:83]
	v_mfma_f32_16x16x32_bf16 v[68:71], v[174:177], v[214:217], v[68:71]
	v_mfma_f32_16x16x32_bf16 v[64:67], v[182:185], v[214:217], v[64:67]
	s_barrier
	s_setprio 0
	s_add_i32 s72, s65, s43
	v_lshl_add_u64 v[150:151], s[36:37], 0, v[130:131]
	s_mov_b32 m0, s72
	s_nop 0
	global_load_lds_dwordx4 v[150:151], off
	s_add_i32 m0, s72, 0x2000
	s_add_u32 s72, s36, 0x40000
	v_lshl_add_u64 v[218:219], s[36:37], 0, v[134:135]
	s_addc_u32 s73, s37, 0
	s_add_i32 s74, s67, s43
	global_load_lds_dwordx4 v[218:219], off
	v_lshl_add_u64 v[220:221], s[72:73], 0, v[130:131]
	s_mov_b32 m0, s74
	v_lshl_add_u64 v[222:223], s[38:39], 0, v[132:133]
	global_load_lds_dwordx4 v[220:221], off
	v_lshl_add_u64 v[220:221], s[72:73], 0, v[134:135]
	s_add_i32 m0, s74, 0x2000
	s_nop 0
	global_load_lds_dwordx4 v[220:221], off
	v_lshl_add_u64 v[220:221], s[38:39], 0, v[128:129]
	s_mov_b32 m0, s31
	s_nop 0
	global_load_lds_dwordx4 v[220:221], off
	s_mov_b32 m0, s46
	s_nop 0
	global_load_lds_dwordx4 v[222:223], off
	ds_read_b128 v[186:189], v157 offset:16384
	ds_read_b128 v[190:193], v157 offset:17408
	ds_read_b128 v[194:197], v157 offset:18432
	ds_read_b128 v[198:201], v157 offset:19456
	ds_read_b128 v[202:205], v157 offset:20480
	ds_read_b128 v[206:209], v157 offset:21504
	ds_read_b128 v[210:213], v157 offset:22528
	ds_read_b128 v[214:217], v157 offset:23552
	s_nop 0
	s_waitcnt vmcnt(8)
	s_waitcnt lgkmcnt(0)
	s_setprio 1
	s_barrier
	v_mfma_f32_16x16x32_bf16 v[60:63], v[146:149], v[186:189], v[60:63]
	v_mfma_f32_16x16x32_bf16 v[56:59], v[162:165], v[186:189], v[56:59]
	v_mfma_f32_16x16x32_bf16 v[44:47], v[146:149], v[194:197], v[44:47]
	v_mfma_f32_16x16x32_bf16 v[40:43], v[162:165], v[194:197], v[40:43]
	v_mfma_f32_16x16x32_bf16 v[28:31], v[146:149], v[202:205], v[28:31]
	v_mfma_f32_16x16x32_bf16 v[24:27], v[162:165], v[202:205], v[24:27]
	v_mfma_f32_16x16x32_bf16 v[12:15], v[146:149], v[210:213], v[12:15]
	v_mfma_f32_16x16x32_bf16 v[8:11], v[162:165], v[210:213], v[8:11]
	v_mfma_f32_16x16x32_bf16 v[60:63], v[158:161], v[190:193], v[60:63]
	v_mfma_f32_16x16x32_bf16 v[56:59], v[166:169], v[190:193], v[56:59]
	v_mfma_f32_16x16x32_bf16 v[44:47], v[158:161], v[198:201], v[44:47]
	v_mfma_f32_16x16x32_bf16 v[40:43], v[166:169], v[198:201], v[40:43]
	v_mfma_f32_16x16x32_bf16 v[28:31], v[158:161], v[206:209], v[28:31]
	v_mfma_f32_16x16x32_bf16 v[24:27], v[166:169], v[206:209], v[24:27]
	v_mfma_f32_16x16x32_bf16 v[12:15], v[158:161], v[214:217], v[12:15]
	v_mfma_f32_16x16x32_bf16 v[8:11], v[166:169], v[214:217], v[8:11]
	s_setprio 0
	s_setprio 1
	v_mfma_f32_16x16x32_bf16 v[52:55], v[170:173], v[186:189], v[52:55]
	v_mfma_f32_16x16x32_bf16 v[48:51], v[178:181], v[186:189], v[48:51]
	v_mfma_f32_16x16x32_bf16 v[36:39], v[170:173], v[194:197], v[36:39]
	v_mfma_f32_16x16x32_bf16 v[32:35], v[178:181], v[194:197], v[32:35]
	v_mfma_f32_16x16x32_bf16 v[20:23], v[170:173], v[202:205], v[20:23]
	v_mfma_f32_16x16x32_bf16 v[16:19], v[178:181], v[202:205], v[16:19]
	v_mfma_f32_16x16x32_bf16 v[4:7], v[170:173], v[210:213], v[4:7]
	v_mfma_f32_16x16x32_bf16 v[0:3], v[178:181], v[210:213], v[0:3]
	v_mfma_f32_16x16x32_bf16 v[52:55], v[174:177], v[190:193], v[52:55]
	v_mfma_f32_16x16x32_bf16 v[48:51], v[182:185], v[190:193], v[48:51]
	v_mfma_f32_16x16x32_bf16 v[36:39], v[174:177], v[198:201], v[36:39]
	v_mfma_f32_16x16x32_bf16 v[32:35], v[182:185], v[198:201], v[32:35]
	v_mfma_f32_16x16x32_bf16 v[20:23], v[174:177], v[206:209], v[20:23]
	v_mfma_f32_16x16x32_bf16 v[16:19], v[182:185], v[206:209], v[16:19]
	v_mfma_f32_16x16x32_bf16 v[4:7], v[174:177], v[214:217], v[4:7]
	v_mfma_f32_16x16x32_bf16 v[0:3], v[182:185], v[214:217], v[0:3]
	s_barrier
	s_setprio 0
	s_add_i32 s72, 0, 0x18000
	s_add_i32 s73, 0, 0x1c000
	s_add_u32 s38, s38, 0x40000
	s_addc_u32 s39, s39, 0
	s_mov_b32 m0, s47
	v_lshl_add_u64 v[224:225], s[38:39], 0, v[128:129]
	global_load_lds_dwordx4 v[224:225], off
	v_lshl_add_u64 v[224:225], s[38:39], 0, v[132:133]
	s_mov_b32 m0, s48
	s_nop 0
	global_load_lds_dwordx4 v[224:225], off
	v_add_u32_e32 v136, s72, v153
	ds_read_b128 v[146:149], v136
	ds_read_b128 v[158:161], v136 offset:1024
	ds_read_b128 v[162:165], v136 offset:2048
	ds_read_b128 v[166:169], v136 offset:3072
	v_add_u32_e32 v136, s73, v153
	ds_read_b128 v[170:173], v136
	ds_read_b128 v[174:177], v136 offset:1024
	ds_read_b128 v[178:181], v136 offset:2048
	ds_read_b128 v[182:185], v136 offset:3072
	ds_read_b128 v[186:189], v157 offset:32768
	ds_read_b128 v[190:193], v157 offset:33792
	ds_read_b128 v[194:197], v157 offset:34816
	ds_read_b128 v[198:201], v157 offset:35840
	ds_read_b128 v[202:205], v157 offset:36864
	ds_read_b128 v[206:209], v157 offset:37888
	ds_read_b128 v[210:213], v157 offset:38912
	ds_read_b128 v[214:217], v157 offset:39936
	s_waitcnt vmcnt(8)
	s_waitcnt lgkmcnt(0)
	s_setprio 1
	s_barrier
	v_mfma_f32_16x16x32_bf16 v[124:127], v[146:149], v[186:189], v[124:127]
	v_mfma_f32_16x16x32_bf16 v[120:123], v[162:165], v[186:189], v[120:123]
	v_mfma_f32_16x16x32_bf16 v[108:111], v[146:149], v[194:197], v[108:111]
	v_mfma_f32_16x16x32_bf16 v[104:107], v[162:165], v[194:197], v[104:107]
	v_mfma_f32_16x16x32_bf16 v[92:95], v[146:149], v[202:205], v[92:95]
	v_mfma_f32_16x16x32_bf16 v[88:91], v[162:165], v[202:205], v[88:91]
	v_mfma_f32_16x16x32_bf16 v[76:79], v[146:149], v[210:213], v[76:79]
	v_mfma_f32_16x16x32_bf16 v[72:75], v[162:165], v[210:213], v[72:75]
	v_mfma_f32_16x16x32_bf16 v[124:127], v[158:161], v[190:193], v[124:127]
	v_mfma_f32_16x16x32_bf16 v[120:123], v[166:169], v[190:193], v[120:123]
	v_mfma_f32_16x16x32_bf16 v[108:111], v[158:161], v[198:201], v[108:111]
	v_mfma_f32_16x16x32_bf16 v[104:107], v[166:169], v[198:201], v[104:107]
	v_mfma_f32_16x16x32_bf16 v[92:95], v[158:161], v[206:209], v[92:95]
	v_mfma_f32_16x16x32_bf16 v[88:91], v[166:169], v[206:209], v[88:91]
	v_mfma_f32_16x16x32_bf16 v[76:79], v[158:161], v[214:217], v[76:79]
	v_mfma_f32_16x16x32_bf16 v[72:75], v[166:169], v[214:217], v[72:75]
	s_setprio 0
	s_setprio 1
	v_mfma_f32_16x16x32_bf16 v[116:119], v[170:173], v[186:189], v[116:119]
	v_mfma_f32_16x16x32_bf16 v[112:115], v[178:181], v[186:189], v[112:115]
	v_mfma_f32_16x16x32_bf16 v[100:103], v[170:173], v[194:197], v[100:103]
	v_mfma_f32_16x16x32_bf16 v[96:99], v[178:181], v[194:197], v[96:99]
	v_mfma_f32_16x16x32_bf16 v[84:87], v[170:173], v[202:205], v[84:87]
	v_mfma_f32_16x16x32_bf16 v[80:83], v[178:181], v[202:205], v[80:83]
	v_mfma_f32_16x16x32_bf16 v[68:71], v[170:173], v[210:213], v[68:71]
	v_mfma_f32_16x16x32_bf16 v[64:67], v[178:181], v[210:213], v[64:67]
	v_mfma_f32_16x16x32_bf16 v[116:119], v[174:177], v[190:193], v[116:119]
	v_mfma_f32_16x16x32_bf16 v[112:115], v[182:185], v[190:193], v[112:115]
	v_mfma_f32_16x16x32_bf16 v[100:103], v[174:177], v[198:201], v[100:103]
	v_mfma_f32_16x16x32_bf16 v[96:99], v[182:185], v[198:201], v[96:99]
	v_mfma_f32_16x16x32_bf16 v[84:87], v[174:177], v[206:209], v[84:87]
	v_mfma_f32_16x16x32_bf16 v[80:83], v[182:185], v[206:209], v[80:83]
	v_mfma_f32_16x16x32_bf16 v[68:71], v[174:177], v[214:217], v[68:71]
	v_mfma_f32_16x16x32_bf16 v[64:67], v[182:185], v[214:217], v[64:67]
	s_barrier
	s_setprio 0
	s_add_i32 s38, s72, s43
	v_lshl_add_u64 v[150:151], v[150:151], 0, s[12:13]
	s_mov_b32 m0, s38
	s_nop 0
	global_load_lds_dwordx4 v[150:151], off
	s_add_i32 m0, s38, 0x2000
	s_add_u32 s36, s36, 0x40080
	v_lshl_add_u64 v[150:151], v[218:219], 0, s[12:13]
	s_addc_u32 s37, s37, 0
	s_add_i32 s38, s73, s43
	global_load_lds_dwordx4 v[150:151], off
	v_lshl_add_u64 v[150:151], s[36:37], 0, v[130:131]
	s_mov_b32 m0, s38
	s_nop 0
	global_load_lds_dwordx4 v[150:151], off
	v_lshl_add_u64 v[150:151], s[36:37], 0, v[134:135]
	s_add_i32 m0, s38, 0x2000
	s_nop 0
	global_load_lds_dwordx4 v[150:151], off
	v_lshl_add_u64 v[150:151], v[220:221], 0, s[12:13]
	s_mov_b32 m0, s60
	s_nop 0
	global_load_lds_dwordx4 v[150:151], off
	v_lshl_add_u64 v[150:151], v[222:223], 0, s[12:13]
	s_mov_b32 m0, s61
	s_nop 0
	global_load_lds_dwordx4 v[150:151], off
	ds_read_b128 v[186:189], v157 offset:49152
	ds_read_b128 v[190:193], v157 offset:50176
	ds_read_b128 v[194:197], v157 offset:51200
	ds_read_b128 v[198:201], v157 offset:52224
	ds_read_b128 v[202:205], v157 offset:53248
	ds_read_b128 v[206:209], v157 offset:54272
	ds_read_b128 v[210:213], v157 offset:55296
	ds_read_b128 v[214:217], v157 offset:56320
	s_waitcnt vmcnt(8)
	s_waitcnt lgkmcnt(0)
	s_setprio 1
	s_barrier
	v_mfma_f32_16x16x32_bf16 v[60:63], v[146:149], v[186:189], v[60:63]
	v_mfma_f32_16x16x32_bf16 v[56:59], v[162:165], v[186:189], v[56:59]
	v_mfma_f32_16x16x32_bf16 v[44:47], v[146:149], v[194:197], v[44:47]
	v_mfma_f32_16x16x32_bf16 v[40:43], v[162:165], v[194:197], v[40:43]
	v_mfma_f32_16x16x32_bf16 v[28:31], v[146:149], v[202:205], v[28:31]
	v_mfma_f32_16x16x32_bf16 v[24:27], v[162:165], v[202:205], v[24:27]
	v_mfma_f32_16x16x32_bf16 v[12:15], v[146:149], v[210:213], v[12:15]
	v_mfma_f32_16x16x32_bf16 v[8:11], v[162:165], v[210:213], v[8:11]
	v_mfma_f32_16x16x32_bf16 v[60:63], v[158:161], v[190:193], v[60:63]
	v_mfma_f32_16x16x32_bf16 v[56:59], v[166:169], v[190:193], v[56:59]
	v_mfma_f32_16x16x32_bf16 v[44:47], v[158:161], v[198:201], v[44:47]
	v_mfma_f32_16x16x32_bf16 v[40:43], v[166:169], v[198:201], v[40:43]
	v_mfma_f32_16x16x32_bf16 v[28:31], v[158:161], v[206:209], v[28:31]
	v_mfma_f32_16x16x32_bf16 v[24:27], v[166:169], v[206:209], v[24:27]
	v_mfma_f32_16x16x32_bf16 v[12:15], v[158:161], v[214:217], v[12:15]
	v_mfma_f32_16x16x32_bf16 v[8:11], v[166:169], v[214:217], v[8:11]
	s_setprio 0
	s_setprio 1
	v_mfma_f32_16x16x32_bf16 v[52:55], v[170:173], v[186:189], v[52:55]
	v_mfma_f32_16x16x32_bf16 v[48:51], v[178:181], v[186:189], v[48:51]
	v_mfma_f32_16x16x32_bf16 v[36:39], v[170:173], v[194:197], v[36:39]
	v_mfma_f32_16x16x32_bf16 v[32:35], v[178:181], v[194:197], v[32:35]
	v_mfma_f32_16x16x32_bf16 v[20:23], v[170:173], v[202:205], v[20:23]
	v_mfma_f32_16x16x32_bf16 v[16:19], v[178:181], v[202:205], v[16:19]
	v_mfma_f32_16x16x32_bf16 v[4:7], v[170:173], v[210:213], v[4:7]
	v_mfma_f32_16x16x32_bf16 v[0:3], v[178:181], v[210:213], v[0:3]
	v_mfma_f32_16x16x32_bf16 v[52:55], v[174:177], v[190:193], v[52:55]
	v_mfma_f32_16x16x32_bf16 v[48:51], v[182:185], v[190:193], v[48:51]
	v_mfma_f32_16x16x32_bf16 v[36:39], v[174:177], v[198:201], v[36:39]
	v_mfma_f32_16x16x32_bf16 v[32:35], v[182:185], v[198:201], v[32:35]
	v_mfma_f32_16x16x32_bf16 v[20:23], v[174:177], v[206:209], v[20:23]
	v_mfma_f32_16x16x32_bf16 v[16:19], v[182:185], v[206:209], v[16:19]
	v_mfma_f32_16x16x32_bf16 v[4:7], v[174:177], v[214:217], v[4:7]
	v_mfma_f32_16x16x32_bf16 v[0:3], v[182:185], v[214:217], v[0:3]
	s_barrier
	s_setprio 0
	s_add_i32 s71, s71, 2
	s_add_u32 s34, s34, 0x100
	s_addc_u32 s35, s35, 0
	s_add_u32 s69, s69, 0x100
	s_addc_u32 s70, s70, 0
	s_cmp_gt_u32 s71, 13
	s_cbranch_scc0 .LBB0_217
	s_and_b64 vcc, exec, s[14:15]
	s_cbranch_vccz .LBB0_220
	s_barrier
